# GEMM1 mode-2 epilogue: the 16 sum-of-squares reductions run four at a time with packed f32 math (same f32 sums, fewer dependent instructions)
# baseline (speedup 1.0000x reference)
.LBB0_203:
	v_mov_b32_e32 v181, 1.0
	v_cndmask_b32_e64 v130, 0, 1, s[34:35]
	v_cmp_ne_u32_e64 s[40:41], 1, v130
	s_andn2_b64 vcc, exec, s[34:35]
	v_mov_b32_e32 v180, v181
	v_mov_b32_e32 v185, v181
	v_mov_b32_e32 v184, v181
	v_mov_b32_e32 v189, v181
	v_mov_b32_e32 v188, v181
	v_mov_b32_e32 v193, v181
	v_mov_b32_e32 v192, v181
	v_mov_b32_e32 v169, v181
	v_mov_b32_e32 v168, v181
	v_mov_b32_e32 v183, v181
	v_mov_b32_e32 v182, v181
	v_mov_b32_e32 v187, v181
	v_mov_b32_e32 v186, v181
	v_mov_b32_e32 v191, v181
	v_mov_b32_e32 v190, v181
	v_mov_b32_e32 v175, v181
	v_mov_b32_e32 v174, v181
	v_mov_b32_e32 v173, v181
	v_mov_b32_e32 v172, v181
	v_mov_b32_e32 v163, v181
	v_mov_b32_e32 v162, v181
	v_mov_b32_e32 v161, v181
	v_mov_b32_e32 v160, v181
	v_mov_b32_e32 v165, v181
	v_mov_b32_e32 v164, v181
	v_mov_b32_e32 v167, v181
	v_mov_b32_e32 v166, v181
	v_mov_b32_e32 v171, v181
	v_mov_b32_e32 v170, v181
	v_mov_b32_e32 v177, v181
	v_mov_b32_e32 v176, v181
	s_cbranch_vccnz .LBB0_237
	v_lshl_add_u64 v[228:229], s[42:43], 0, v[146:147]
	v_mov_b32_e32 v230, v156
	v_mov_b32_e32 v231, v147
	v_lshl_add_u64 v[228:229], v[228:229], 0, v[230:231]
	v_bfe_u32 v230, v0, 7, 1
	v_mul_u32_u24_e32 v230, s70, v230
	v_lshlrev_b32_e32 v230, 2, v230
	v_lshl_add_u64 v[228:229], v[228:229], 0, v[230:231]
	global_load_dwordx4 v[200:203], v[228:229], off offset:16
	global_load_dwordx4 v[204:207], v[228:229], off
	v_mov_b32_e32 v230, s70
	v_lshlrev_b32_e32 v230, 3, v230
	v_lshl_add_u64 v[232:233], v[228:229], 0, v[230:231]
	global_load_dwordx4 v[216:219], v[232:233], off offset:16
	global_load_dwordx4 v[224:227], v[232:233], off
	v_pk_mul_f32 v[234:235], v[114:115], v[114:115]
	v_pk_mul_f32 v[236:237], v[98:99], v[98:99]
	v_pk_mul_f32 v[238:239], v[82:83], v[82:83]
	v_pk_mul_f32 v[240:241], v[66:67], v[66:67]
	v_pk_fma_f32 v[234:235], v[116:117], v[116:117], v[234:235]
	v_pk_fma_f32 v[236:237], v[100:101], v[100:101], v[236:237]
	v_pk_fma_f32 v[238:239], v[84:85], v[84:85], v[238:239]
	v_pk_fma_f32 v[240:241], v[68:69], v[68:69], v[240:241]
	v_pk_fma_f32 v[234:235], v[122:123], v[122:123], v[234:235]
	v_pk_fma_f32 v[236:237], v[106:107], v[106:107], v[236:237]
	v_pk_fma_f32 v[238:239], v[90:91], v[90:91], v[238:239]
	v_pk_fma_f32 v[240:241], v[74:75], v[74:75], v[240:241]
	v_pk_fma_f32 v[234:235], v[124:125], v[124:125], v[234:235]
	v_pk_fma_f32 v[236:237], v[108:109], v[108:109], v[236:237]
	v_pk_fma_f32 v[238:239], v[92:93], v[92:93], v[238:239]
	v_pk_fma_f32 v[240:241], v[76:77], v[76:77], v[240:241]
	v_add_f32_e32 v234, v234, v235
	v_add_f32_e32 v236, v236, v237
	v_add_f32_e32 v238, v238, v239
	v_add_f32_e32 v240, v240, v241
	v_mov_b32_e32 v242, v234
	v_mov_b32_e32 v243, v236
	v_mov_b32_e32 v244, v238
	v_mov_b32_e32 v245, v240
	v_permlane16_swap_b32_e32 v242, v234
	v_permlane16_swap_b32_e32 v243, v236
	v_permlane16_swap_b32_e32 v244, v238
	v_permlane16_swap_b32_e32 v245, v240
	v_add_f32_e32 v234, v234, v242
	v_add_f32_e32 v236, v236, v243
	v_add_f32_e32 v238, v238, v244
	v_add_f32_e32 v240, v240, v245
	v_mov_b32_e32 v242, v234
	v_mov_b32_e32 v243, v236
	v_mov_b32_e32 v244, v238
	v_mov_b32_e32 v245, v240
	v_permlane32_swap_b32_e32 v242, v234
	v_permlane32_swap_b32_e32 v243, v236
	v_permlane32_swap_b32_e32 v244, v238
	v_permlane32_swap_b32_e32 v245, v240
	v_add_f32_e32 v132, v234, v242
	v_add_f32_e32 v133, v236, v243
	v_add_f32_e32 v168, v238, v244
	v_add_f32_e32 v169, v240, v245
	s_and_saveexec_b64 s[34:35], s[4:5]
	ds_write_b32 v221, v132
	ds_write_b32 v221, v133 offset:64
	ds_write_b32 v221, v168 offset:128
	ds_write_b32 v221, v169 offset:192
	s_or_b64 exec, exec, s[34:35]
	v_pk_mul_f32 v[234:235], v[50:51], v[50:51]
	v_pk_mul_f32 v[236:237], v[34:35], v[34:35]
	v_pk_mul_f32 v[238:239], v[18:19], v[18:19]
	v_pk_mul_f32 v[240:241], v[2:3], v[2:3]
	v_pk_fma_f32 v[234:235], v[52:53], v[52:53], v[234:235]
	v_pk_fma_f32 v[236:237], v[36:37], v[36:37], v[236:237]
	v_pk_fma_f32 v[238:239], v[20:21], v[20:21], v[238:239]
	v_pk_fma_f32 v[240:241], v[4:5], v[4:5], v[240:241]
	v_pk_fma_f32 v[234:235], v[58:59], v[58:59], v[234:235]
	v_pk_fma_f32 v[236:237], v[42:43], v[42:43], v[236:237]
	v_pk_fma_f32 v[238:239], v[26:27], v[26:27], v[238:239]
	v_pk_fma_f32 v[240:241], v[10:11], v[10:11], v[240:241]
	v_pk_fma_f32 v[234:235], v[60:61], v[60:61], v[234:235]
	v_pk_fma_f32 v[236:237], v[44:45], v[44:45], v[236:237]
	v_pk_fma_f32 v[238:239], v[28:29], v[28:29], v[238:239]
	v_pk_fma_f32 v[240:241], v[12:13], v[12:13], v[240:241]
	v_add_f32_e32 v234, v234, v235
	v_add_f32_e32 v236, v236, v237
	v_add_f32_e32 v238, v238, v239
	v_add_f32_e32 v240, v240, v241
	v_mov_b32_e32 v242, v234
	v_mov_b32_e32 v243, v236
	v_mov_b32_e32 v244, v238
	v_mov_b32_e32 v245, v240
	v_permlane16_swap_b32_e32 v242, v234
	v_permlane16_swap_b32_e32 v243, v236
	v_permlane16_swap_b32_e32 v244, v238
	v_permlane16_swap_b32_e32 v245, v240
	v_add_f32_e32 v234, v234, v242
	v_add_f32_e32 v236, v236, v243
	v_add_f32_e32 v238, v238, v244
	v_add_f32_e32 v240, v240, v245
	v_mov_b32_e32 v242, v234
	v_mov_b32_e32 v243, v236
	v_mov_b32_e32 v244, v238
	v_mov_b32_e32 v245, v240
	v_permlane32_swap_b32_e32 v242, v234
	v_permlane32_swap_b32_e32 v243, v236
	v_permlane32_swap_b32_e32 v244, v238
	v_permlane32_swap_b32_e32 v245, v240
	v_add_f32_e32 v172, v234, v242
	v_add_f32_e32 v173, v236, v243
	v_add_f32_e32 v174, v238, v244
	v_add_f32_e32 v175, v240, v245
	s_and_saveexec_b64 s[34:35], s[4:5]
	ds_write_b32 v254, v172
	ds_write_b32 v221, v173 offset:320
	ds_write_b32 v221, v174 offset:384
	ds_write_b32 v221, v175 offset:448
	s_or_b64 exec, exec, s[34:35]
	v_pk_mul_f32 v[234:235], v[118:119], v[118:119]
	v_pk_mul_f32 v[236:237], v[102:103], v[102:103]
	v_pk_mul_f32 v[238:239], v[86:87], v[86:87]
	v_pk_mul_f32 v[240:241], v[70:71], v[70:71]
	v_pk_fma_f32 v[234:235], v[120:121], v[120:121], v[234:235]
	v_pk_fma_f32 v[236:237], v[104:105], v[104:105], v[236:237]
	v_pk_fma_f32 v[238:239], v[88:89], v[88:89], v[238:239]
	v_pk_fma_f32 v[240:241], v[72:73], v[72:73], v[240:241]
	v_pk_fma_f32 v[234:235], v[126:127], v[126:127], v[234:235]
	v_pk_fma_f32 v[236:237], v[110:111], v[110:111], v[236:237]
	v_pk_fma_f32 v[238:239], v[94:95], v[94:95], v[238:239]
	v_pk_fma_f32 v[240:241], v[78:79], v[78:79], v[240:241]
	v_pk_fma_f32 v[234:235], v[128:129], v[128:129], v[234:235]
	v_pk_fma_f32 v[236:237], v[112:113], v[112:113], v[236:237]
	v_pk_fma_f32 v[238:239], v[96:97], v[96:97], v[238:239]
	v_pk_fma_f32 v[240:241], v[80:81], v[80:81], v[240:241]
	v_add_f32_e32 v234, v234, v235
	v_add_f32_e32 v236, v236, v237
	v_add_f32_e32 v238, v238, v239
	v_add_f32_e32 v240, v240, v241
	v_mov_b32_e32 v242, v234
	v_mov_b32_e32 v243, v236
	v_mov_b32_e32 v244, v238
	v_mov_b32_e32 v245, v240
	v_permlane16_swap_b32_e32 v242, v234
	v_permlane16_swap_b32_e32 v243, v236
	v_permlane16_swap_b32_e32 v244, v238
	v_permlane16_swap_b32_e32 v245, v240
	v_add_f32_e32 v234, v234, v242
	v_add_f32_e32 v236, v236, v243
	v_add_f32_e32 v238, v238, v244
	v_add_f32_e32 v240, v240, v245
	v_mov_b32_e32 v242, v234
	v_mov_b32_e32 v243, v236
	v_mov_b32_e32 v244, v238
	v_mov_b32_e32 v245, v240
	v_permlane32_swap_b32_e32 v242, v234
	v_permlane32_swap_b32_e32 v243, v236
	v_permlane32_swap_b32_e32 v244, v238
	v_permlane32_swap_b32_e32 v245, v240
	v_add_f32_e32 v136, v234, v242
	v_add_f32_e32 v137, v236, v243
	v_add_f32_e32 v158, v238, v244
	v_add_f32_e32 v159, v240, v245
	s_and_saveexec_b64 s[34:35], s[4:5]
	ds_write_b32 v208, v136
	ds_write_b32 v221, v137 offset:576
	ds_write_b32 v221, v158 offset:640
	ds_write_b32 v221, v159 offset:704
	s_or_b64 exec, exec, s[34:35]
	v_pk_mul_f32 v[234:235], v[54:55], v[54:55]
	v_pk_mul_f32 v[236:237], v[38:39], v[38:39]
	v_pk_mul_f32 v[238:239], v[22:23], v[22:23]
	v_pk_mul_f32 v[240:241], v[6:7], v[6:7]
	v_pk_fma_f32 v[234:235], v[56:57], v[56:57], v[234:235]
	v_pk_fma_f32 v[236:237], v[40:41], v[40:41], v[236:237]
	v_pk_fma_f32 v[238:239], v[24:25], v[24:25], v[238:239]
	v_pk_fma_f32 v[240:241], v[8:9], v[8:9], v[240:241]
	v_pk_fma_f32 v[234:235], v[62:63], v[62:63], v[234:235]
	v_pk_fma_f32 v[236:237], v[46:47], v[46:47], v[236:237]
	v_pk_fma_f32 v[238:239], v[30:31], v[30:31], v[238:239]
	v_pk_fma_f32 v[240:241], v[14:15], v[14:15], v[240:241]
	v_pk_fma_f32 v[234:235], v[64:65], v[64:65], v[234:235]
	v_pk_fma_f32 v[236:237], v[48:49], v[48:49], v[236:237]
	v_pk_fma_f32 v[238:239], v[32:33], v[32:33], v[238:239]
	v_pk_fma_f32 v[240:241], v[16:17], v[16:17], v[240:241]
	v_add_f32_e32 v234, v234, v235
	v_add_f32_e32 v236, v236, v237
	v_add_f32_e32 v238, v238, v239
	v_add_f32_e32 v240, v240, v241
	v_mov_b32_e32 v242, v234
	v_mov_b32_e32 v243, v236
	v_mov_b32_e32 v244, v238
	v_mov_b32_e32 v245, v240
	v_permlane16_swap_b32_e32 v242, v234
	v_permlane16_swap_b32_e32 v243, v236
	v_permlane16_swap_b32_e32 v244, v238
	v_permlane16_swap_b32_e32 v245, v240
	v_add_f32_e32 v234, v234, v242
	v_add_f32_e32 v236, v236, v243
	v_add_f32_e32 v238, v238, v244
	v_add_f32_e32 v240, v240, v245
	v_mov_b32_e32 v242, v234
	v_mov_b32_e32 v243, v236
	v_mov_b32_e32 v244, v238
	v_mov_b32_e32 v245, v240
	v_permlane32_swap_b32_e32 v242, v234
	v_permlane32_swap_b32_e32 v243, v236
	v_permlane32_swap_b32_e32 v244, v238
	v_permlane32_swap_b32_e32 v245, v240
	v_add_f32_e32 v134, v234, v242
	v_add_f32_e32 v135, v236, v243
	v_add_f32_e32 v130, v238, v244
	v_add_f32_e32 v131, v240, v245
	s_and_saveexec_b64 s[34:35], s[4:5]
	ds_write_b32 v198, v134
	ds_write_b32 v221, v135 offset:832
	ds_write_b32 v221, v130 offset:896
	ds_write_b32 v196, v131
	s_or_b64 exec, exec, s[34:35]
	s_or_b64 exec, exec, s[34:35]
	v_lshl_add_u64 v[160:161], s[42:43], 0, v[146:147]
	v_mov_b32_e32 v157, v147
	v_lshl_add_u64 v[160:161], v[160:161], 0, v[156:157]
	v_bfe_u32 v157, v0, 7, 1
	v_mul_u32_u24_e32 v157, s70, v157
	v_lshlrev_b32_e32 v162, 2, v157
	v_mov_b32_e32 v163, v147
	v_lshl_add_u64 v[170:171], v[160:161], 0, v[162:163]
	s_waitcnt vmcnt(0) lgkmcnt(0)
	s_barrier
	v_mov_b32_e32 v160, v200
	v_mov_b32_e32 v161, v201
	v_mov_b32_e32 v162, v202
	v_mov_b32_e32 v163, v203
	v_mov_b32_e32 v176, v204
	v_mov_b32_e32 v177, v205
	v_mov_b32_e32 v178, v206
	v_mov_b32_e32 v179, v207
	s_mov_b32 s14, 0x358637bd
	s_lshl_b32 s70, s70, 3
	v_lshl_add_u64 v[170:171], v[170:171], 0, s[70:71]
	s_waitcnt vmcnt(1)
	v_pk_mul_f32 v[162:163], s[30:31], v[162:163] op_sel_hi:[0,1]
	s_waitcnt vmcnt(0)
	v_pk_mul_f32 v[166:167], v[176:177], s[30:31] op_sel_hi:[1,0]
	ds_read2_b32 v[176:177], v211 offset1:16
	v_pk_mul_f32 v[164:165], v[178:179], s[30:31] op_sel_hi:[1,0]
	v_pk_mul_f32 v[160:161], s[30:31], v[160:161] op_sel_hi:[0,1]
	s_waitcnt lgkmcnt(0)
	v_pk_add_f32 v[176:177], v[132:133], v[176:177]
	v_mov_b64_e32 v[132:133], s[14:15]
	v_pk_fma_f32 v[176:177], v[176:177], s[8:9], v[132:133] op_sel_hi:[1,0,0]
	s_nop 0
	v_mul_f32_e32 v157, 0x4b800000, v176
	v_cmp_gt_f32_e64 s[42:43], s11, v176
	v_cmp_gt_f32_e32 vcc, s11, v177
	s_nop 0
	v_cndmask_b32_e64 v157, v176, v157, s[42:43]
	v_rsq_f32_e32 v176, v157
	v_mul_f32_e32 v157, 0x4b800000, v177
	v_cndmask_b32_e32 v157, v177, v157, vcc
	v_rsq_f32_e32 v177, v157
	s_nop 0
	v_pk_mul_f32 v[178:179], v[176:177], s[10:11] op_sel_hi:[1,0]
	s_nop 0
	v_cndmask_b32_e64 v190, v176, v178, s[42:43]
	v_cndmask_b32_e32 v191, v177, v179, vcc
	ds_read2_b32 v[176:177], v211 offset0:32 offset1:48
	s_waitcnt lgkmcnt(0)
	v_pk_add_f32 v[168:169], v[168:169], v[176:177]
	s_nop 0
	v_pk_fma_f32 v[168:169], v[168:169], s[8:9], v[132:133] op_sel_hi:[1,0,0]
	s_nop 0
	v_mul_f32_e32 v157, 0x4b800000, v168
	v_cmp_gt_f32_e64 s[42:43], s11, v168
	v_cmp_gt_f32_e32 vcc, s11, v169
	s_nop 0
	v_cndmask_b32_e64 v157, v168, v157, s[42:43]
	v_rsq_f32_e32 v168, v157
	v_mul_f32_e32 v157, 0x4b800000, v169
	v_cndmask_b32_e32 v157, v169, v157, vcc
	v_rsq_f32_e32 v169, v157
	s_nop 0
	v_pk_mul_f32 v[176:177], v[168:169], s[10:11] op_sel_hi:[1,0]
	s_nop 0
	v_cndmask_b32_e64 v186, v168, v176, s[42:43]
	v_cndmask_b32_e32 v187, v169, v177, vcc
	ds_read_b32 v168, v212
	ds_read2_b32 v[176:177], v211 offset0:80 offset1:96
	ds_read2_b32 v[178:179], v211 offset0:112 offset1:144
	s_waitcnt lgkmcnt(1)
	v_mov_b32_e32 v169, v176
	v_pk_add_f32 v[168:169], v[172:173], v[168:169]
	s_nop 0
	v_pk_fma_f32 v[168:169], v[168:169], s[8:9], v[132:133] op_sel_hi:[1,0,0]
	s_nop 0
	v_mul_f32_e32 v157, 0x4b800000, v168
	v_cmp_gt_f32_e64 s[42:43], s11, v168
	v_cmp_gt_f32_e32 vcc, s11, v169
	s_nop 0
	v_cndmask_b32_e64 v157, v168, v157, s[42:43]
	v_rsq_f32_e32 v168, v157
	v_mul_f32_e32 v157, 0x4b800000, v169
	v_cndmask_b32_e32 v157, v169, v157, vcc
	v_rsq_f32_e32 v169, v157
	s_nop 0
	v_pk_mul_f32 v[172:173], v[168:169], s[10:11] op_sel_hi:[1,0]
	s_nop 0
	v_cndmask_b32_e64 v182, v168, v172, s[42:43]
	v_cndmask_b32_e32 v183, v169, v173, vcc
	v_mov_b32_e32 v168, v177
	s_waitcnt lgkmcnt(0)
	v_mov_b32_e32 v169, v178
	v_pk_add_f32 v[168:169], v[174:175], v[168:169]
	s_nop 0
	v_pk_fma_f32 v[168:169], v[168:169], s[8:9], v[132:133] op_sel_hi:[1,0,0]
	s_nop 0
	v_mul_f32_e32 v157, 0x4b800000, v168
	v_cmp_gt_f32_e64 s[42:43], s11, v168
	v_cmp_gt_f32_e32 vcc, s11, v169
	s_nop 0
	v_cndmask_b32_e64 v157, v168, v157, s[42:43]
	v_rsq_f32_e32 v168, v157
	v_mul_f32_e32 v157, 0x4b800000, v169
	v_cndmask_b32_e32 v157, v169, v157, vcc
	v_rsq_f32_e32 v169, v157
	s_nop 0
	v_pk_mul_f32 v[172:173], v[168:169], s[10:11] op_sel_hi:[1,0]
	s_nop 0
	v_cndmask_b32_e64 v168, v168, v172, s[42:43]
	v_cndmask_b32_e32 v169, v169, v173, vcc
	v_mov_b32_e32 v192, v216
	v_mov_b32_e32 v193, v217
	v_mov_b32_e32 v194, v218
	v_mov_b32_e32 v195, v219
	s_nop 0
	v_mov_b32_e32 v170, v224
	v_mov_b32_e32 v171, v225
	v_mov_b32_e32 v172, v226
	v_mov_b32_e32 v173, v227
	ds_read_b32 v178, v213
	s_waitcnt lgkmcnt(0)
	v_pk_add_f32 v[136:137], v[136:137], v[178:179]
	s_nop 0
	v_pk_fma_f32 v[136:137], v[136:137], s[8:9], v[132:133] op_sel_hi:[1,0,0]
	s_waitcnt vmcnt(1)
	v_pk_mul_f32 v[176:177], s[30:31], v[192:193] op_sel_hi:[0,1]
	v_mul_f32_e32 v157, 0x4b800000, v136
	v_cmp_gt_f32_e64 s[42:43], s11, v136
	v_cmp_gt_f32_e32 vcc, s11, v137
	s_waitcnt vmcnt(0)
	v_pk_mul_f32 v[174:175], s[30:31], v[172:173] op_sel_hi:[0,1]
	v_cndmask_b32_e64 v136, v136, v157, s[42:43]
	v_mul_f32_e32 v157, 0x4b800000, v137
	v_cndmask_b32_e32 v137, v137, v157, vcc
	v_rsq_f32_e32 v136, v136
	v_rsq_f32_e32 v137, v137
	v_pk_mul_f32 v[172:173], s[30:31], v[170:171] op_sel_hi:[0,1]
	v_pk_mul_f32 v[170:171], s[30:31], v[194:195] op_sel_hi:[0,1]
	v_pk_mul_f32 v[178:179], v[136:137], s[10:11] op_sel_hi:[1,0]
	s_nop 0
	v_cndmask_b32_e64 v192, v136, v178, s[42:43]
	v_cndmask_b32_e32 v193, v137, v179, vcc
	ds_read2_b32 v[136:137], v211 offset0:160 offset1:176
	s_waitcnt lgkmcnt(0)
	v_pk_add_f32 v[136:137], v[158:159], v[136:137]
	s_nop 0
	v_pk_fma_f32 v[136:137], v[136:137], s[8:9], v[132:133] op_sel_hi:[1,0,0]
	s_nop 0
	v_mul_f32_e32 v157, 0x4b800000, v136
	v_cmp_gt_f32_e64 s[42:43], s11, v136
	v_cmp_gt_f32_e32 vcc, s11, v137
	s_nop 0
	v_cndmask_b32_e64 v136, v136, v157, s[42:43]
	v_mul_f32_e32 v157, 0x4b800000, v137
	v_cndmask_b32_e32 v137, v137, v157, vcc
	v_rsq_f32_e32 v136, v136
	v_rsq_f32_e32 v137, v137
	s_nop 0
	v_pk_mul_f32 v[158:159], v[136:137], s[10:11] op_sel_hi:[1,0]
	s_nop 0
	v_cndmask_b32_e64 v188, v136, v158, s[42:43]
	v_cndmask_b32_e32 v189, v137, v159, vcc
	ds_read_b32 v158, v214
	ds_read2_b32 v[136:137], v211 offset0:208 offset1:224
	s_waitcnt lgkmcnt(0)
	v_mov_b32_e32 v159, v136
	v_pk_add_f32 v[134:135], v[134:135], v[158:159]
	s_nop 0
	v_pk_fma_f32 v[134:135], v[134:135], s[8:9], v[132:133] op_sel_hi:[1,0,0]
	s_nop 0
	v_mul_f32_e32 v136, 0x4b800000, v134
	v_cmp_gt_f32_e64 s[42:43], s11, v134
	v_cmp_gt_f32_e32 vcc, s11, v135
	s_nop 0
	v_cndmask_b32_e64 v134, v134, v136, s[42:43]
	v_mul_f32_e32 v136, 0x4b800000, v135
	v_cndmask_b32_e32 v135, v135, v136, vcc
	v_rsq_f32_e32 v134, v134
	v_rsq_f32_e32 v135, v135
	s_nop 0
	v_pk_mul_f32 v[158:159], v[134:135], s[10:11] op_sel_hi:[1,0]
	s_nop 0
	v_cndmask_b32_e32 v185, v135, v159, vcc
	ds_read_b32 v135, v215
	v_cndmask_b32_e64 v184, v134, v158, s[42:43]
	v_mov_b32_e32 v134, v137
	s_waitcnt lgkmcnt(0)
	v_pk_add_f32 v[130:131], v[130:131], v[134:135]
	s_nop 0
	v_pk_fma_f32 v[130:131], v[130:131], s[8:9], v[132:133] op_sel_hi:[1,0,0]
	s_nop 0
	v_mul_f32_e32 v132, 0x4b800000, v130
	v_cmp_gt_f32_e64 s[42:43], s11, v130
	v_cmp_gt_f32_e32 vcc, s11, v131
	s_nop 0
	v_cndmask_b32_e64 v130, v130, v132, s[42:43]
	v_mul_f32_e32 v132, 0x4b800000, v131
	v_cndmask_b32_e32 v131, v131, v132, vcc
	v_rsq_f32_e32 v130, v130
	v_rsq_f32_e32 v131, v131
	s_nop 0
	v_pk_mul_f32 v[132:133], v[130:131], s[10:11] op_sel_hi:[1,0]
	s_nop 0
	v_cndmask_b32_e64 v180, v130, v132, s[42:43]
	v_cndmask_b32_e32 v181, v131, v133, vcc
